# speedup vs baseline: 1.0064x; 1.0064x over previous
; __global__ void __launch_bounds__(NTHR, 2) hymba_fwd(Args args) {
;     ...
;     for (int ph = lo; ph < hi; ++ph) {
;         int l = ph / NPH; const int k = ph % NPH;
;         if (k == 3 || k == 11) continue;
;         asm volatile("" : "+s"(l));
;         int G = gridDim.x, bid = blockIdx.x; asm volatile("" : "+s"(G), "+s"(bid));
;         typedef __attribute__((address_space(4))) const unsigned char* kptr_t;
;         kptr_t kp = (kptr_t)__builtin_amdgcn_kernarg_segment_ptr(); asm volatile("" : "+s"(kp));
;         int tid = threadIdx.x; asm volatile("" : "+v"(tid));
;         const int lane = tid & 63, wave = __builtin_amdgcn_readfirstlane(tid >> 6);
;         const int gw = bid * NWAVES + wave, NGW = G * NWAVES;
;         unsigned char* ws = *(unsigned char* const __attribute__((address_space(4)))*)(kp + 376);
;         float* xout = *(float* const __attribute__((address_space(4)))*)(kp + 368);
.LBB0_20:
	s_lshr_b32 s5, s54, 1
	s_mul_hi_i32 s0, s5, 0x92492493
	s_add_i32 s0, s0, s5
	s_lshr_b32 s1, s0, 31
	s_ashr_i32 s0, s0, 3
	s_add_i32 s4, s0, s1
	s_mul_i32 s0, s4, 14
	s_sub_i32 s5, s5, s0
	s_cmp_eq_u32 s5, 1
	s_cselect_b32 s0, 1, 0
	s_cmp_eq_u32 s5, 4
	s_cselect_b32 s1, 1, 0
	s_or_b32 s0, s0, s1
	s_cmp_eq_u32 s5, 7
	s_cselect_b32 s1, 1, 0
	s_or_b32 s0, s0, s1
	s_cmp_eq_u32 s5, 12
	s_cselect_b32 s1, 1, 0
	s_cmp_eq_u32 s4, 0
	s_cselect_b32 s1, s1, 0
	s_or_b32 s0, s0, s1
	s_bitcmp1_b32 s54, 0
	s_cbranch_scc1 .Lhdr_rep1
	s_cmp_eq_u32 s5, 0
	s_cselect_b32 s1, 1, 0
	s_cmp_eq_u32 s4, 1
	s_cselect_b32 s1, s1, 0
	s_or_b32 s0, s0, s1
	v_writelane_b32 v255, s0, 62
	s_mov_b32 s0, 0
	s_mov_b32 s1, 0xa07f
	v_writelane_b32 v255, s0, 61
	v_writelane_b32 v255, s1, 59
	s_movk_i32 s0, 0x2c00
	s_cmp_eq_u32 s4, 0
	s_cselect_b32 s0, s0, 0
	s_mov_b32 s1, 0x9fff
	v_writelane_b32 v255, s0, 57
	v_writelane_b32 v255, s1, 56
	s_branch .Lhdr_common

; #define SREP(bit) for (int rep_ = 0; rep_ < (((SUBDUP >> (bit)) & 1) ? 2 : 1); ++rep_)
; __global__ void __launch_bounds__(NTHR, 2) hymba_fwd(Args args) {
;     ...
;             SREP(5) for (int u = bid; u < 32 * 16; u += G) s5_unit<true>(tid, ldsf, P, L, WSP(f32x2, WS_E), WSP(float, WS_VF), WSP(bf16, WS_VB), u);
.LBB0_253:
	v_readlane_b32 s0, v254, 38
	s_add_i32 s30, s30, s0
	s_cmp_eq_u32 s0, 0x100
	s_cselect_b32 s1, 15, 0
	s_xor_b32 s30, s30, s1
	s_lshl_b32 s28, s30, 3
	s_cmpk_gt_i32 s30, 0x1ff
	v_readlane_b32 s1, v254, 43
	s_cbranch_scc1 .LBB0_306
